# final rmsnorm pass: 8 iterations of loads in flight per thread (counted vmcnt, gain vector hoisted) instead of one load-wait-store per iteration
# speedup vs baseline: 1.0052x; 1.0052x over previous
; #define PHASE_BEGIN if (ph >= lo && ph < hi) { KParams kp = kparams(); unsigned char* ws = kp->ws; (void)ws; int tidp = threadIdx.x; asm volatile("" : "+v"(tidp)); int bid = blockIdx.x; asm volatile("" : "+s"(bid)); (void)tidp; (void)bid;
; __global__ void __launch_bounds__(512, 2) nsa_fwd(Params P_unused) {
;     ...
;     PHASE_BEGIN {
;         const float* ssf = WSP(const float, WS_SS) + (size_t)(2 * DEPTH) * T; const float* fg = kp->in[16]; float* out = kp->out;
;         for (int i = bid * 512 + tidp; i < T * (DM / 4); i += G * 512) {
;             const int row = i >> 9, c4 = i & 511;
;             const float rstd = rsqrtf(ssf[row] * (1.0f / DM) + EPS);
;             const f32x4 gq = *(const f32x4*)(fg + 4 * c4);
.LBB0_1549:
	s_cmp_lt_i32 s44, 24
	s_cselect_b64 s[6:7], -1, 0
	s_cmp_gt_i32 s45, 23
	s_cselect_b64 s[0:1], -1, 0
	s_and_b64 s[0:1], s[6:7], s[0:1]
	s_and_b64 vcc, exec, s[0:1]
	s_cbranch_vccz .LBB0_1554
	s_waitcnt lgkmcnt(0)
	s_mov_b64 s[14:15], s[48:49]
	s_mov_b32 s0, 0x800000
	v_lshl_add_u32 v0, s89, 9, v226
	v_cmp_gt_i32_e32 vcc, s0, v0
	s_and_saveexec_b64 s[12:13], vcc
	s_cbranch_execz .LBB0_1553
	s_load_dwordx2 s[2:3], s[14:15], 0x90
	s_load_dwordx4 s[8:11], s[14:15], 0x80
	v_ashrrev_i32_e32 v1, 31, v0
	v_mov_b32_e32 v4, 0x358637bd
	s_mov_b32 s1, 0x7fffff
	s_waitcnt lgkmcnt(0)
	s_add_u32 s14, s2, 0x39e40000
	v_mov_b32_e32 v2, s10
	v_mov_b32_e32 v3, s11
	v_lshl_add_u64 v[2:3], v[0:1], 4, v[2:3]
	v_lshlrev_b32_e32 v1, 2, v226
	s_addc_u32 s15, s3, 0
	v_lshl_add_u32 v1, s89, 11, v1
	s_mov_b64 s[2:3], 0
	s_cmp_lg_u32 s42, 0x20000
	s_cbranch_scc1 .LBB0_1552
	v_and_b32_e32 v10, 0x7fc, v1
	v_lshlrev_b32_e32 v10, 2, v10
	global_load_dwordx4 v[10:13], v10, s[8:9]
; __global__ void __launch_bounds__(512, 2) nsa_fwd(Params P_unused) {
;     ...
;         for (int i = bid * 512 + tidp; i < T * (DM / 4); i += G * 512) {
;             const int row = i >> 9, c4 = i & 511;
;             const float rstd = rsqrtf(ssf[row] * (1.0f / DM) + EPS);
;             const f32x4 gq = *(const f32x4*)(fg + 4 * c4);
;             f32x4 v = *(f32x4*)(out + (size_t)i * 4);
;             v = v * rstd * gq;
;             *(f32x4*)(out + (size_t)i * 4) = v;
;         }
.Lfin_pass:
	v_lshl_add_u64 v[18:19], v[2:3], 0, s[46:47]
	v_lshl_add_u64 v[20:21], v[18:19], 0, s[46:47]
	v_lshl_add_u64 v[22:23], v[20:21], 0, s[46:47]
	v_lshl_add_u64 v[24:25], v[22:23], 0, s[46:47]
	v_lshl_add_u64 v[26:27], v[24:25], 0, s[46:47]
	v_lshl_add_u64 v[28:29], v[26:27], 0, s[46:47]
	v_lshl_add_u64 v[30:31], v[28:29], 0, s[46:47]
	v_ashrrev_i32_e32 v112, 9, v0
	v_ashrrev_i32_e32 v113, 31, v112
	v_lshl_add_u64 v[112:113], v[112:113], 2, s[14:15]
	global_load_dword v40, v[112:113], off
	global_load_dwordx4 v[48:51], v[2:3], off
	v_add_u32_e32 v0, s42, v0
	v_ashrrev_i32_e32 v114, 9, v0
	v_ashrrev_i32_e32 v115, 31, v114
	v_lshl_add_u64 v[114:115], v[114:115], 2, s[14:15]
	global_load_dword v41, v[114:115], off
	global_load_dwordx4 v[52:55], v[18:19], off
	v_add_u32_e32 v0, s42, v0
	v_ashrrev_i32_e32 v116, 9, v0
	v_ashrrev_i32_e32 v117, 31, v116
	v_lshl_add_u64 v[116:117], v[116:117], 2, s[14:15]
	global_load_dword v42, v[116:117], off
	global_load_dwordx4 v[56:59], v[20:21], off
	v_add_u32_e32 v0, s42, v0
	v_ashrrev_i32_e32 v118, 9, v0
	v_ashrrev_i32_e32 v119, 31, v118
	v_lshl_add_u64 v[118:119], v[118:119], 2, s[14:15]
	global_load_dword v43, v[118:119], off
	global_load_dwordx4 v[60:63], v[22:23], off
	v_add_u32_e32 v0, s42, v0
	v_ashrrev_i32_e32 v120, 9, v0
	v_ashrrev_i32_e32 v121, 31, v120
	v_lshl_add_u64 v[120:121], v[120:121], 2, s[14:15]
	global_load_dword v44, v[120:121], off
	global_load_dwordx4 v[64:67], v[24:25], off
	v_add_u32_e32 v0, s42, v0
	v_ashrrev_i32_e32 v122, 9, v0
	v_ashrrev_i32_e32 v123, 31, v122
	v_lshl_add_u64 v[122:123], v[122:123], 2, s[14:15]
	global_load_dword v45, v[122:123], off
	global_load_dwordx4 v[68:71], v[26:27], off
	v_add_u32_e32 v0, s42, v0
	v_ashrrev_i32_e32 v124, 9, v0
	v_ashrrev_i32_e32 v125, 31, v124
	v_lshl_add_u64 v[124:125], v[124:125], 2, s[14:15]
	global_load_dword v46, v[124:125], off
	global_load_dwordx4 v[72:75], v[28:29], off
	v_add_u32_e32 v0, s42, v0
	v_ashrrev_i32_e32 v126, 9, v0
	v_ashrrev_i32_e32 v127, 31, v126
	v_lshl_add_u64 v[126:127], v[126:127], 2, s[14:15]
	global_load_dword v47, v[126:127], off
	global_load_dwordx4 v[76:79], v[30:31], off
	v_add_u32_e32 v0, s42, v0
	s_waitcnt vmcnt(14)
	v_fmamk_f32 v5, v40, 0x3a000000, v4
	v_mul_f32_e32 v14, 0x4b800000, v5
	v_cmp_gt_f32_e32 vcc, s0, v5
	s_nop 1
	v_cndmask_b32_e32 v5, v5, v14, vcc
	v_rsq_f32_e32 v5, v5
	s_nop 0
	v_mul_f32_e32 v14, 0x45800000, v5
	v_cndmask_b32_e32 v14, v5, v14, vcc
	v_pk_mul_f32 v[48:49], v[48:49], v[14:15] op_sel_hi:[1,0]
	v_pk_mul_f32 v[50:51], v[50:51], v[14:15] op_sel_hi:[1,0]
	v_pk_mul_f32 v[48:49], v[10:11], v[48:49]
	v_pk_mul_f32 v[50:51], v[12:13], v[50:51]
	s_waitcnt vmcnt(12)
	v_fmamk_f32 v5, v41, 0x3a000000, v4
	v_mul_f32_e32 v14, 0x4b800000, v5
	v_cmp_gt_f32_e32 vcc, s0, v5
	s_nop 1
	v_cndmask_b32_e32 v5, v5, v14, vcc
	v_rsq_f32_e32 v5, v5
	s_nop 0
	v_mul_f32_e32 v14, 0x45800000, v5
	v_cndmask_b32_e32 v14, v5, v14, vcc
	v_pk_mul_f32 v[52:53], v[52:53], v[14:15] op_sel_hi:[1,0]
	v_pk_mul_f32 v[54:55], v[54:55], v[14:15] op_sel_hi:[1,0]
	v_pk_mul_f32 v[52:53], v[10:11], v[52:53]
	v_pk_mul_f32 v[54:55], v[12:13], v[54:55]
	s_waitcnt vmcnt(10)
	v_fmamk_f32 v5, v42, 0x3a000000, v4
	v_mul_f32_e32 v14, 0x4b800000, v5
	v_cmp_gt_f32_e32 vcc, s0, v5
	s_nop 1
	v_cndmask_b32_e32 v5, v5, v14, vcc
	v_rsq_f32_e32 v5, v5
	s_nop 0
	v_mul_f32_e32 v14, 0x45800000, v5
	v_cndmask_b32_e32 v14, v5, v14, vcc
	v_pk_mul_f32 v[56:57], v[56:57], v[14:15] op_sel_hi:[1,0]
	v_pk_mul_f32 v[58:59], v[58:59], v[14:15] op_sel_hi:[1,0]
	v_pk_mul_f32 v[56:57], v[10:11], v[56:57]
	v_pk_mul_f32 v[58:59], v[12:13], v[58:59]
	s_waitcnt vmcnt(8)
	v_fmamk_f32 v5, v43, 0x3a000000, v4
	v_mul_f32_e32 v14, 0x4b800000, v5
	v_cmp_gt_f32_e32 vcc, s0, v5
	s_nop 1
	v_cndmask_b32_e32 v5, v5, v14, vcc
	v_rsq_f32_e32 v5, v5
	s_nop 0
	v_mul_f32_e32 v14, 0x45800000, v5
	v_cndmask_b32_e32 v14, v5, v14, vcc
	v_pk_mul_f32 v[60:61], v[60:61], v[14:15] op_sel_hi:[1,0]
	v_pk_mul_f32 v[62:63], v[62:63], v[14:15] op_sel_hi:[1,0]
	v_pk_mul_f32 v[60:61], v[10:11], v[60:61]
	v_pk_mul_f32 v[62:63], v[12:13], v[62:63]
	s_waitcnt vmcnt(6)
	v_fmamk_f32 v5, v44, 0x3a000000, v4
	v_mul_f32_e32 v14, 0x4b800000, v5
	v_cmp_gt_f32_e32 vcc, s0, v5
	s_nop 1
	v_cndmask_b32_e32 v5, v5, v14, vcc
	v_rsq_f32_e32 v5, v5
	s_nop 0
	v_mul_f32_e32 v14, 0x45800000, v5
	v_cndmask_b32_e32 v14, v5, v14, vcc
	v_pk_mul_f32 v[64:65], v[64:65], v[14:15] op_sel_hi:[1,0]
	v_pk_mul_f32 v[66:67], v[66:67], v[14:15] op_sel_hi:[1,0]
	v_pk_mul_f32 v[64:65], v[10:11], v[64:65]
	v_pk_mul_f32 v[66:67], v[12:13], v[66:67]
	s_waitcnt vmcnt(4)
	v_fmamk_f32 v5, v45, 0x3a000000, v4
	v_mul_f32_e32 v14, 0x4b800000, v5
	v_cmp_gt_f32_e32 vcc, s0, v5
	s_nop 1
	v_cndmask_b32_e32 v5, v5, v14, vcc
	v_rsq_f32_e32 v5, v5
	s_nop 0
	v_mul_f32_e32 v14, 0x45800000, v5
	v_cndmask_b32_e32 v14, v5, v14, vcc
	v_pk_mul_f32 v[68:69], v[68:69], v[14:15] op_sel_hi:[1,0]
	v_pk_mul_f32 v[70:71], v[70:71], v[14:15] op_sel_hi:[1,0]
	v_pk_mul_f32 v[68:69], v[10:11], v[68:69]
	v_pk_mul_f32 v[70:71], v[12:13], v[70:71]
	s_waitcnt vmcnt(2)
	v_fmamk_f32 v5, v46, 0x3a000000, v4
	v_mul_f32_e32 v14, 0x4b800000, v5
	v_cmp_gt_f32_e32 vcc, s0, v5
	s_nop 1
	v_cndmask_b32_e32 v5, v5, v14, vcc
	v_rsq_f32_e32 v5, v5
	s_nop 0
	v_mul_f32_e32 v14, 0x45800000, v5
	v_cndmask_b32_e32 v14, v5, v14, vcc
	v_pk_mul_f32 v[72:73], v[72:73], v[14:15] op_sel_hi:[1,0]
	v_pk_mul_f32 v[74:75], v[74:75], v[14:15] op_sel_hi:[1,0]
	v_pk_mul_f32 v[72:73], v[10:11], v[72:73]
	v_pk_mul_f32 v[74:75], v[12:13], v[74:75]
	s_waitcnt vmcnt(0)
	v_fmamk_f32 v5, v47, 0x3a000000, v4
	v_mul_f32_e32 v14, 0x4b800000, v5
	v_cmp_gt_f32_e32 vcc, s0, v5
	s_nop 1
	v_cndmask_b32_e32 v5, v5, v14, vcc
	v_rsq_f32_e32 v5, v5
	s_nop 0
	v_mul_f32_e32 v14, 0x45800000, v5
	v_cndmask_b32_e32 v14, v5, v14, vcc
	v_pk_mul_f32 v[76:77], v[76:77], v[14:15] op_sel_hi:[1,0]
	v_pk_mul_f32 v[78:79], v[78:79], v[14:15] op_sel_hi:[1,0]
	v_pk_mul_f32 v[76:77], v[10:11], v[76:77]
	v_pk_mul_f32 v[78:79], v[12:13], v[78:79]
	global_store_dwordx4 v[2:3], v[48:51], off
	global_store_dwordx4 v[18:19], v[52:55], off
	global_store_dwordx4 v[20:21], v[56:59], off
	global_store_dwordx4 v[22:23], v[60:63], off
	global_store_dwordx4 v[24:25], v[64:67], off
	global_store_dwordx4 v[26:27], v[68:71], off
	global_store_dwordx4 v[28:29], v[72:75], off
	global_store_dwordx4 v[30:31], v[76:79], off
	v_lshl_add_u64 v[2:3], v[30:31], 0, s[46:47]
	s_add_i32 s2, s2, 1
	s_cmp_lt_u32 s2, 8
	s_cbranch_scc1 .Lfin_pass
	s_branch .LBB0_1553
